# v54: v37 + attention row maxima of both query sub-blocks reduced with shared permlane swaps (lower/upper half-wave carry one each)
# speedup vs baseline: 1.0021x; 1.0017x over previous
; #define LAS __attribute__((address_space(3)))
; __device__ __forceinline__ void attn_phase(LAS unsigned char* lds, const bf16_t* Q, const bf16_t* KN, const bf16_t* P, const bf16_t* VT, bf16_t* CAT, int bid, int G, const int tid) {
;     ...
;                     float mx = -INFINITY;
; #pragma unroll
;                     for (int kb = 0; kb < 4; ++kb) mx = fmaxf(mx, fmaxf(fmaxf(s[kb][qi][0], s[kb][qi][1]), fmaxf(s[kb][qi][2], s[kb][qi][3])));
;                     mx = fmaxf(mx, __shfl_xor(mx, 16)); mx = fmaxf(mx, __shfl_xor(mx, 32));
;                     const float mnew = fmaxf(mrow[qi], mx);
;                     const float alpha = __builtin_amdgcn_exp2f(mrow[qi] - mnew);
;                     mrow[qi] = mnew;
;                     float ps = 0.f;
; #pragma unroll
;                     for (int kb = 0; kb < 4; ++kb)
; #pragma unroll
;                         for (int j = 0; j < 4; ++j) { const float e = __builtin_amdgcn_exp2f(s[kb][qi][j] - mnew); s[kb][qi][j] = e; ps += e; }
;                     lrow[qi] = lrow[qi] * alpha + ps;
; #pragma unroll
;                     for (int d = 0; d < 8; ++d) o[d][qi] = o[d][qi] * alpha;
; #pragma unroll
;                     for (int cc = 0; cc < 2; ++cc) {
;                         u32x4 t; t.x = cvt_pk_bf16(s[2 * cc][qi][0], s[2 * cc][qi][1]); t.y = cvt_pk_bf16(s[2 * cc][qi][2], s[2 * cc][qi][3]);
;                         t.z = cvt_pk_bf16(s[2 * cc + 1][qi][0], s[2 * cc + 1][qi][1]); t.w = cvt_pk_bf16(s[2 * cc + 1][qi][2], s[2 * cc + 1][qi][3]);
;                         pf[qi][cc] = __builtin_bit_cast(bf16x8, t);
;                     }
;                 }
; #pragma unroll
;                 for (int cc = 0; cc < 2; ++cc)
; #pragma unroll
;                     for (int d = 0; d < 8; ++d) {
;                         const LAS unsigned char* vp = buf + KBYTES + ((d * 16 + fr) * VS + 32 * cc + 4 * fq) * 2;
;                         const u32x2 v0 = *(const LAS u32x2*)vp, v1 = *(const LAS u32x2*)(vp + 32);
;                         const u32x4 vv = {v0.x, v0.y, v1.x, v1.y};
;                         const bf16x8 vf = __builtin_bit_cast(bf16x8, vv);
;                         o[d][0] = __builtin_amdgcn_mfma_f32_16x16x32_bf16(vf, pf[0][cc], o[d][0], 0, 0, 0);
;                         o[d][1] = __builtin_amdgcn_mfma_f32_16x16x32_bf16(vf, pf[1][cc], o[d][1], 0, 0, 0);
.LBB0_144:
	v_add3_u32 v174, s35, v180, v243
	v_add_u32_e32 v175, 0x6400, v174
	ds_read2_b64 v[208:211], v175 offset1:4
	v_add_u32_e32 v172, 0x6d00, v174
	ds_read2_b64 v[212:215], v172 offset1:4
	v_add_u32_e32 v173, 0x7600, v174
	ds_read2_b64 v[216:219], v173 offset1:4
	v_add_u32_e32 v175, 0x7f00, v174
	ds_read2_b64 v[220:223], v175 offset1:4
	v_add_u32_e32 v172, 0x8800, v174
	ds_read2_b64 v[224:227], v172 offset1:4
	v_max3_f32 v170, v132, v133, v134
	v_max3_f32 v204, v148, v149, v150
	v_max3_f32 v171, v135, v136, v137
	v_max3_f32 v205, v151, v156, v157
	v_max3_f32 v170, v170, v138, v139
	v_max3_f32 v204, v204, v158, v159
	v_max3_f32 v171, v171, v140, v141
	v_max3_f32 v205, v205, v152, v153
	v_max3_f32 v170, v170, v142, v143
	v_max3_f32 v204, v204, v154, v155
	v_max3_f32 v171, v171, v144, v145
	v_max3_f32 v205, v205, v160, v161
	v_max3_f32 v170, v170, v146, v147
	v_max3_f32 v204, v204, v162, v163
	v_max_f32_e32 v170, v170, v171
	v_max_f32_e32 v204, v204, v205
	s_nop 1
	v_permlane32_swap_b32 v170, v204
	v_max_f32_e32 v170, v170, v204
	v_mov_b32_e32 v171, v170
	s_nop 1
	v_permlane16_swap_b32 v170, v171
	v_max_f32_e32 v170, v170, v171
	v_mov_b32_e32 v171, v170
	s_nop 1
	v_permlane32_swap_b32 v170, v171
	v_max_f32_e32 v245, v207, v170
	v_max_f32_e32 v246, v206, v171
	v_sub_f32_e32 v171, v207, v245
	v_sub_f32_e32 v205, v206, v246
	v_exp_f32_e32 v230, v171
	v_exp_f32_e32 v252, v205
	v_pk_add_f32 v[132:133], v[132:133], v[244:245] op_sel:[0,1] op_sel_hi:[1,1] neg_lo:[0,1] neg_hi:[0,1]
	v_pk_add_f32 v[148:149], v[148:149], v[246:247] op_sel_hi:[1,0] neg_lo:[0,1] neg_hi:[0,1]
	v_pk_add_f32 v[134:135], v[134:135], v[244:245] op_sel:[0,1] op_sel_hi:[1,1] neg_lo:[0,1] neg_hi:[0,1]
	v_pk_add_f32 v[150:151], v[150:151], v[246:247] op_sel_hi:[1,0] neg_lo:[0,1] neg_hi:[0,1]
	v_pk_add_f32 v[136:137], v[136:137], v[244:245] op_sel:[0,1] op_sel_hi:[1,1] neg_lo:[0,1] neg_hi:[0,1]
	v_pk_add_f32 v[156:157], v[156:157], v[246:247] op_sel_hi:[1,0] neg_lo:[0,1] neg_hi:[0,1]
	v_pk_add_f32 v[138:139], v[138:139], v[244:245] op_sel:[0,1] op_sel_hi:[1,1] neg_lo:[0,1] neg_hi:[0,1]
	v_pk_add_f32 v[158:159], v[158:159], v[246:247] op_sel_hi:[1,0] neg_lo:[0,1] neg_hi:[0,1]
	v_exp_f32_e32 v132, v132
	v_exp_f32_e32 v148, v148
	v_exp_f32_e32 v133, v133
	v_exp_f32_e32 v149, v149
	v_exp_f32_e32 v134, v134
	v_exp_f32_e32 v150, v150
	v_exp_f32_e32 v135, v135
	v_exp_f32_e32 v151, v151
	v_exp_f32_e32 v136, v136
	v_exp_f32_e32 v156, v156
	v_exp_f32_e32 v137, v137
	v_exp_f32_e32 v157, v157
	v_exp_f32_e32 v138, v138
	v_exp_f32_e32 v158, v158
	v_exp_f32_e32 v139, v139
	v_exp_f32_e32 v159, v159
	v_pk_mul_f32 v[32:33], v[32:33], v[230:231] op_sel_hi:[1,0]
	v_pk_mul_f32 v[34:35], v[34:35], v[230:231] op_sel_hi:[1,0]
	v_pk_mul_f32 v[0:1], v[0:1], v[252:253] op_sel_hi:[1,0]
	v_pk_mul_f32 v[2:3], v[2:3], v[252:253] op_sel_hi:[1,0]
	v_pk_add_f32 v[228:229], v[132:133], v[134:135]
	v_pk_add_f32 v[170:171], v[148:149], v[150:151]
	v_pk_add_f32 v[228:229], v[228:229], v[136:137]
	v_pk_add_f32 v[170:171], v[170:171], v[156:157]
	v_pk_add_f32 v[228:229], v[228:229], v[138:139]
	v_pk_add_f32 v[170:171], v[170:171], v[158:159]
	v_cvt_pk_bf16_f32 v132, v132, v133
	v_cvt_pk_bf16_f32 v133, v134, v135
	v_cvt_pk_bf16_f32 v134, v136, v137
	v_cvt_pk_bf16_f32 v135, v138, v139
	v_cvt_pk_bf16_f32 v148, v148, v149
	v_cvt_pk_bf16_f32 v149, v150, v151
	v_cvt_pk_bf16_f32 v150, v156, v157
	v_cvt_pk_bf16_f32 v151, v158, v159
	v_add_u32_e32 v173, 0x9100, v174
	ds_read2_b64 v[136:139], v173 offset1:4
	v_add_u32_e32 v175, 0x9a00, v174
	ds_read2_b64 v[156:159], v175 offset1:4
	v_pk_mul_f32 v[36:37], v[36:37], v[230:231] op_sel_hi:[1,0]
	v_pk_mul_f32 v[38:39], v[38:39], v[230:231] op_sel_hi:[1,0]
	v_pk_mul_f32 v[4:5], v[4:5], v[252:253] op_sel_hi:[1,0]
	v_pk_mul_f32 v[6:7], v[6:7], v[252:253] op_sel_hi:[1,0]
	s_waitcnt lgkmcnt(6)
	v_mfma_f32_16x16x32_bf16 v[32:35], v[208:211], v[132:135], v[32:35]
	v_mfma_f32_16x16x32_bf16 v[0:3], v[208:211], v[148:151], v[0:3]
	v_add_u32_e32 v172, 0xa300, v174
	ds_read2_b64 v[208:211], v172 offset1:4
	v_pk_mul_f32 v[40:41], v[40:41], v[230:231] op_sel_hi:[1,0]
	v_pk_mul_f32 v[42:43], v[42:43], v[230:231] op_sel_hi:[1,0]
	v_pk_mul_f32 v[8:9], v[8:9], v[252:253] op_sel_hi:[1,0]
	v_pk_mul_f32 v[10:11], v[10:11], v[252:253] op_sel_hi:[1,0]
	v_pk_add_f32 v[140:141], v[140:141], v[244:245] op_sel:[0,1] op_sel_hi:[1,1] neg_lo:[0,1] neg_hi:[0,1]
	v_pk_add_f32 v[152:153], v[152:153], v[246:247] op_sel_hi:[1,0] neg_lo:[0,1] neg_hi:[0,1]
	v_pk_add_f32 v[142:143], v[142:143], v[244:245] op_sel:[0,1] op_sel_hi:[1,1] neg_lo:[0,1] neg_hi:[0,1]
	v_pk_add_f32 v[154:155], v[154:155], v[246:247] op_sel_hi:[1,0] neg_lo:[0,1] neg_hi:[0,1]
	v_pk_add_f32 v[144:145], v[144:145], v[244:245] op_sel:[0,1] op_sel_hi:[1,1] neg_lo:[0,1] neg_hi:[0,1]
	v_pk_add_f32 v[160:161], v[160:161], v[246:247] op_sel_hi:[1,0] neg_lo:[0,1] neg_hi:[0,1]
	s_waitcnt lgkmcnt(6)
	v_mfma_f32_16x16x32_bf16 v[36:39], v[212:215], v[132:135], v[36:39]
	v_mfma_f32_16x16x32_bf16 v[4:7], v[212:215], v[148:151], v[4:7]
	v_add_u32_e32 v173, 0x6400, v174
	ds_read2_b64 v[212:215], v173 offset0:8 offset1:12
	v_pk_mul_f32 v[44:45], v[44:45], v[230:231] op_sel_hi:[1,0]
	v_pk_mul_f32 v[46:47], v[46:47], v[230:231] op_sel_hi:[1,0]
	v_pk_mul_f32 v[12:13], v[12:13], v[252:253] op_sel_hi:[1,0]
	v_pk_mul_f32 v[14:15], v[14:15], v[252:253] op_sel_hi:[1,0]
	v_pk_add_f32 v[146:147], v[146:147], v[244:245] op_sel:[0,1] op_sel_hi:[1,1] neg_lo:[0,1] neg_hi:[0,1]
	v_pk_add_f32 v[162:163], v[162:163], v[246:247] op_sel_hi:[1,0] neg_lo:[0,1] neg_hi:[0,1]
	v_exp_f32_e32 v140, v140
	v_exp_f32_e32 v152, v152
	v_exp_f32_e32 v141, v141
	v_exp_f32_e32 v153, v153
	s_waitcnt lgkmcnt(6)
; #define LAS __attribute__((address_space(3)))
; __device__ __forceinline__ unsigned cvt_pk_bf16(float lo, float hi) { unsigned r; asm("v_cvt_pk_bf16_f32 %0, %1, %2" : "=v"(r) : "v"(lo), "v"(hi)); return r; }
; __device__ __forceinline__ void attn_phase(LAS unsigned char* lds, const bf16_t* Q, const bf16_t* KN, const bf16_t* P, const bf16_t* VT, bf16_t* CAT, int bid, int G, const int tid) {
;     ...
;                     float ps = 0.f;
; #pragma unroll
;                     for (int kb = 0; kb < 4; ++kb)
; #pragma unroll
;                         for (int j = 0; j < 4; ++j) { const float e = __builtin_amdgcn_exp2f(s[kb][qi][j] - mnew); s[kb][qi][j] = e; ps += e; }
;                     lrow[qi] = lrow[qi] * alpha + ps;
; #pragma unroll
;                     for (int d = 0; d < 8; ++d) o[d][qi] = o[d][qi] * alpha;
; #pragma unroll
;                     for (int cc = 0; cc < 2; ++cc) {
;                         u32x4 t; t.x = cvt_pk_bf16(s[2 * cc][qi][0], s[2 * cc][qi][1]); t.y = cvt_pk_bf16(s[2 * cc][qi][2], s[2 * cc][qi][3]);
;                         t.z = cvt_pk_bf16(s[2 * cc + 1][qi][0], s[2 * cc + 1][qi][1]); t.w = cvt_pk_bf16(s[2 * cc + 1][qi][2], s[2 * cc + 1][qi][3]);
;                         pf[qi][cc] = __builtin_bit_cast(bf16x8, t);
;                     }
;                 }
; #pragma unroll
;                 for (int cc = 0; cc < 2; ++cc)
; #pragma unroll
;                     for (int d = 0; d < 8; ++d) {
;                         const LAS unsigned char* vp = buf + KBYTES + ((d * 16 + fr) * VS + 32 * cc + 4 * fq) * 2;
;                         const u32x2 v0 = *(const LAS u32x2*)vp, v1 = *(const LAS u32x2*)(vp + 32);
;                         const u32x4 vv = {v0.x, v0.y, v1.x, v1.y};
;                         const bf16x8 vf = __builtin_bit_cast(bf16x8, vv);
;                         o[d][0] = __builtin_amdgcn_mfma_f32_16x16x32_bf16(vf, pf[0][cc], o[d][0], 0, 0, 0);
;                         o[d][1] = __builtin_amdgcn_mfma_f32_16x16x32_bf16(vf, pf[1][cc], o[d][1], 0, 0, 0);
	v_mfma_f32_16x16x32_bf16 v[40:43], v[216:219], v[132:135], v[40:43]
	v_mfma_f32_16x16x32_bf16 v[8:11], v[216:219], v[148:151], v[8:11]
	v_add_u32_e32 v175, 0x6d00, v174
	ds_read2_b64 v[216:219], v175 offset0:8 offset1:12
	v_pk_mul_f32 v[52:53], v[52:53], v[230:231] op_sel_hi:[1,0]
	v_pk_mul_f32 v[54:55], v[54:55], v[230:231] op_sel_hi:[1,0]
	v_pk_mul_f32 v[16:17], v[16:17], v[252:253] op_sel_hi:[1,0]
	v_pk_mul_f32 v[18:19], v[18:19], v[252:253] op_sel_hi:[1,0]
	v_exp_f32_e32 v142, v142
	v_exp_f32_e32 v154, v154
	v_exp_f32_e32 v143, v143
	v_exp_f32_e32 v155, v155
	v_exp_f32_e32 v144, v144
	v_exp_f32_e32 v160, v160
	s_waitcnt lgkmcnt(6)
	v_mfma_f32_16x16x32_bf16 v[44:47], v[220:223], v[132:135], v[44:47]
	v_mfma_f32_16x16x32_bf16 v[12:15], v[220:223], v[148:151], v[12:15]
	v_add_u32_e32 v172, 0x7600, v174
	ds_read2_b64 v[220:223], v172 offset0:8 offset1:12
	v_pk_mul_f32 v[48:49], v[48:49], v[230:231] op_sel_hi:[1,0]
	v_pk_mul_f32 v[50:51], v[50:51], v[230:231] op_sel_hi:[1,0]
	v_pk_mul_f32 v[20:21], v[20:21], v[252:253] op_sel_hi:[1,0]
	v_pk_mul_f32 v[22:23], v[22:23], v[252:253] op_sel_hi:[1,0]
	v_exp_f32_e32 v145, v145
	v_exp_f32_e32 v161, v161
	v_exp_f32_e32 v146, v146
	v_exp_f32_e32 v162, v162
	v_exp_f32_e32 v147, v147
	v_exp_f32_e32 v163, v163
	s_waitcnt lgkmcnt(6)
	v_mfma_f32_16x16x32_bf16 v[52:55], v[224:227], v[132:135], v[52:55]
	v_mfma_f32_16x16x32_bf16 v[16:19], v[224:227], v[148:151], v[16:19]
	v_add_u32_e32 v173, 0x7f00, v174
	ds_read2_b64 v[224:227], v173 offset0:8 offset1:12
	v_pk_mul_f32 v[56:57], v[56:57], v[230:231] op_sel_hi:[1,0]
	v_pk_mul_f32 v[58:59], v[58:59], v[230:231] op_sel_hi:[1,0]
	v_pk_mul_f32 v[24:25], v[24:25], v[252:253] op_sel_hi:[1,0]
	v_pk_mul_f32 v[26:27], v[26:27], v[252:253] op_sel_hi:[1,0]
	v_pk_add_f32 v[228:229], v[228:229], v[140:141]
	v_pk_add_f32 v[170:171], v[170:171], v[152:153]
	v_pk_add_f32 v[228:229], v[228:229], v[142:143]
	v_pk_add_f32 v[170:171], v[170:171], v[154:155]
	v_pk_add_f32 v[228:229], v[228:229], v[144:145]
	v_pk_add_f32 v[170:171], v[170:171], v[160:161]
	s_waitcnt lgkmcnt(6)
	v_mfma_f32_16x16x32_bf16 v[48:51], v[136:139], v[132:135], v[48:51]
	v_mfma_f32_16x16x32_bf16 v[20:23], v[136:139], v[148:151], v[20:23]
	v_add_u32_e32 v175, 0x8800, v174
	ds_read2_b64 v[136:139], v175 offset0:8 offset1:12
	v_pk_mul_f32 v[60:61], v[60:61], v[230:231] op_sel_hi:[1,0]
	v_pk_mul_f32 v[62:63], v[62:63], v[230:231] op_sel_hi:[1,0]
	v_pk_mul_f32 v[28:29], v[28:29], v[252:253] op_sel_hi:[1,0]
	v_pk_mul_f32 v[30:31], v[30:31], v[252:253] op_sel_hi:[1,0]
	v_pk_add_f32 v[228:229], v[228:229], v[146:147]
	v_pk_add_f32 v[170:171], v[170:171], v[162:163]
	v_add_f32_e32 v228, v228, v229
	v_add_f32_e32 v170, v170, v171
	v_cvt_pk_bf16_f32 v140, v140, v141
	v_cvt_pk_bf16_f32 v141, v142, v143
	s_waitcnt lgkmcnt(6)
	v_mfma_f32_16x16x32_bf16 v[56:59], v[156:159], v[132:135], v[56:59]
	v_mfma_f32_16x16x32_bf16 v[24:27], v[156:159], v[148:151], v[24:27]
	v_add_u32_e32 v172, 0x9100, v174
	ds_read2_b64 v[156:159], v172 offset0:8 offset1:12
	v_cvt_pk_bf16_f32 v142, v144, v145
	v_cvt_pk_bf16_f32 v143, v146, v147
	v_cvt_pk_bf16_f32 v152, v152, v153
	v_cvt_pk_bf16_f32 v153, v154, v155
	v_cvt_pk_bf16_f32 v154, v160, v161
	v_cvt_pk_bf16_f32 v155, v162, v163
	s_waitcnt lgkmcnt(6)
	v_mfma_f32_16x16x32_bf16 v[60:63], v[208:211], v[132:135], v[60:63]
	v_mfma_f32_16x16x32_bf16 v[28:31], v[208:211], v[148:151], v[28:31]
	v_add_u32_e32 v173, 0x9a00, v174
	ds_read2_b64 v[208:211], v173 offset0:8 offset1:12
	v_fma_f32 v203, v203, v230, v228
	v_fma_f32 v202, v202, v252, v170
	v_mov_b32_e32 v207, v245
	v_mov_b32_e32 v206, v246
	s_waitcnt lgkmcnt(6)
	v_mfma_f32_16x16x32_bf16 v[32:35], v[212:215], v[140:143], v[32:35]
	v_mfma_f32_16x16x32_bf16 v[0:3], v[212:215], v[152:155], v[0:3]
	v_add_u32_e32 v175, 0xa300, v174
	ds_read2_b64 v[212:215], v175 offset0:8 offset1:12
	s_waitcnt lgkmcnt(6)
	v_mfma_f32_16x16x32_bf16 v[36:39], v[216:219], v[140:143], v[36:39]
	v_mfma_f32_16x16x32_bf16 v[4:7], v[216:219], v[152:155], v[4:7]
	s_waitcnt lgkmcnt(5)
	v_mfma_f32_16x16x32_bf16 v[40:43], v[220:223], v[140:143], v[40:43]
	v_mfma_f32_16x16x32_bf16 v[8:11], v[220:223], v[152:155], v[8:11]
	s_waitcnt lgkmcnt(4)
	v_mfma_f32_16x16x32_bf16 v[44:47], v[224:227], v[140:143], v[44:47]
	v_mfma_f32_16x16x32_bf16 v[12:15], v[224:227], v[152:155], v[12:15]
	s_waitcnt lgkmcnt(3)
	v_mfma_f32_16x16x32_bf16 v[52:55], v[136:139], v[140:143], v[52:55]
	v_mfma_f32_16x16x32_bf16 v[16:19], v[136:139], v[152:155], v[16:19]
	s_waitcnt lgkmcnt(2)
	v_mfma_f32_16x16x32_bf16 v[48:51], v[156:159], v[140:143], v[48:51]
	v_mfma_f32_16x16x32_bf16 v[20:23], v[156:159], v[152:155], v[20:23]
	s_waitcnt lgkmcnt(1)
	v_mfma_f32_16x16x32_bf16 v[56:59], v[208:211], v[140:143], v[56:59]
	v_mfma_f32_16x16x32_bf16 v[24:27], v[208:211], v[152:155], v[24:27]
	s_waitcnt lgkmcnt(0)
	v_mfma_f32_16x16x32_bf16 v[60:63], v[212:215], v[140:143], v[60:63]
	v_mfma_f32_16x16x32_bf16 v[28:31], v[212:215], v[152:155], v[28:31]
